# attention phase: three intra-XCD groups with unit orders [A0 A1 B C] / [A0 B C A1] / [B C A0 A1] (power mixing)
# speedup vs baseline: 1.0222x; 1.0046x over previous
.LBB0_473:
	v_writelane_b32 v252, s76, 29
	s_nop 1
	v_writelane_b32 v252, s77, 30
	s_or_b64 exec, exec, s[0:1]
	s_mov_b64 s[0:1], 0
	s_waitcnt lgkmcnt(0)
	s_barrier
	s_add_u32 s76, s96, s0
	s_addc_u32 s77, s97, s1
	v_readlane_b32 s0, v253, 34
	v_readlane_b32 s1, v253, 35
	s_andn2_b64 vcc, exec, s[0:1]
	s_cbranch_vccnz .LBB0_484
	s_lshr_b32 s0, s52, 3
	s_mul_i32 s1, s0, 0x5556
	s_lshr_b32 s1, s1, 16
	s_mul_i32 s1, s1, 3
	s_sub_u32 s0, s0, s1
	s_mov_b32 s32, 0
	s_cmp_eq_u32 s0, 0
	s_cbranch_scc1 .Lat_A
	s_mov_b32 s32, 4
	s_cmp_eq_u32 s0, 1
	s_cbranch_scc1 .Lat_A
	s_mov_b32 s32, 1
	s_branch .LBB0_484
.Lat_A:
	v_readlane_b32 s4, v252, 29
	s_lshl_b32 s90, s4, 6
	s_lshl_b32 s0, s4, 7
	s_add_u32 s10, s76, 0x2000000
	s_addc_u32 s11, s77, 0
	s_add_u32 s12, s76, 0x1000000
	s_addc_u32 s13, s77, 0
	s_lshl_b64 s[2:3], s[90:91], 2
	s_add_u32 s2, s76, s2
	s_addc_u32 s3, s77, s3
	v_readlane_b32 s5, v252, 30
	s_add_u32 s14, s2, 0x10adbb00
	s_mov_b32 s2, s4
	v_cvt_f32_u32_e32 v0, s4
	s_mov_b32 s5, s91
	s_addc_u32 s15, s3, 0
	v_writelane_b32 v252, s2, 29
	v_mul_f32_e32 v0, 0xbe99999a, v0
	v_mul_f32_e32 v0, 0x3fb8aa3b, v0
	v_writelane_b32 v252, s3, 30
	s_lshl_b64 s[2:3], s[4:5], 2
	s_add_u32 s2, s76, s2
	s_addc_u32 s3, s77, s3
	s_add_u32 s4, s2, 0x10ad8000
	s_addc_u32 s5, s3, 0
	v_exp_f32_e32 v0, v0
	s_add_u32 s16, s76, 0x9000000
	s_addc_u32 s17, s77, 0
	s_mov_b32 s1, s91
	s_add_u32 s18, s76, 0xd000000
	s_addc_u32 s19, s77, 0
	s_lshl_b64 s[0:1], s[0:1], 2
	v_readlane_b32 s20, v253, 0
	v_fmamk_f32 v0, v0, 0x3f19999a, v225
	v_readlane_b32 s21, v253, 1
	s_add_u32 s6, s20, s0
	v_add_f32_e32 v162, 1.0, v0
	s_addc_u32 s7, s21, s1
	v_readlane_b32 s20, v253, 61
	s_mov_b32 s21, s52
	v_readlane_b32 s22, v253, 2
	v_readlane_b32 s23, v253, 3
	v_readlane_b32 s24, v253, 4
	v_readlane_b32 s25, v253, 5
	v_readlane_b32 s26, v253, 6
	v_readlane_b32 s27, v253, 7
	s_cmp_eq_u32 s32, 17
	s_cbranch_scc0 .Lat_noadv
	s_add_i32 s21, s21, s98
	s_add_i32 s20, s20, s67

.LBB0_475:
	s_or_b64 exec, exec, s[0:1]
	s_waitcnt lgkmcnt(0)
	v_add_u32_e32 v72, s9, v194
	ds_read_b128 v[64:67], v72
	ds_read_b128 v[68:71], v72 offset:32
	global_load_dword v109, v195, s[4:5]
	s_lshl_b32 s1, s23, 14
	s_lshl_b32 s0, s22, 1
	s_waitcnt lgkmcnt(1)
	v_rcp_f32_e32 v106, v64
	v_rcp_f32_e32 v105, v65
	v_rcp_f32_e32 v104, v66
	v_rcp_f32_e32 v103, v67
	ds_read_b128 v[64:67], v72 offset:64
	s_add_u32 s22, s16, s0
	s_addc_u32 s23, s17, 0
	s_waitcnt lgkmcnt(1)
	v_rcp_f32_e32 v102, v68
	v_rcp_f32_e32 v101, v69
	s_waitcnt lgkmcnt(0)
	v_rcp_f32_e32 v98, v64
	v_rcp_f32_e32 v97, v65
	v_rcp_f32_e32 v96, v66
	v_rcp_f32_e32 v95, v67
	ds_read_b128 v[64:67], v72 offset:96
	v_rcp_f32_e32 v100, v70
	v_rcp_f32_e32 v99, v71
	s_add_i32 s1, s1, 0
	v_lshlrev_b32_e32 v110, 11, v164
	s_waitcnt lgkmcnt(0)
	v_rcp_f32_e32 v92, v66
	v_or_b32_e32 v66, s8, v166
	v_rcp_f32_e32 v94, v64
	v_lshlrev_b32_e32 v64, 3, v165
	v_lshrrev_b32_e32 v107, 4, v66
	v_and_b32_e32 v108, 0x78, v64
	v_or_b32_e32 v66, s3, v107
	v_rcp_f32_e32 v91, v67
	v_lshlrev_b32_e32 v194, 1, v108
	v_ashrrev_i32_e32 v67, 31, v66
	v_rcp_f32_e32 v93, v65
	v_lshl_add_u64 v[64:65], s[22:23], 0, v[194:195]
	v_lshlrev_b64 v[86:87], 11, v[66:67]
	v_lshl_add_u64 v[66:67], v[64:65], 0, v[86:87]
	v_or_b32_e32 v90, 8, v107
	global_load_dwordx4 v[76:79], v[66:67], off
	v_or_b32_e32 v66, s3, v90
	v_ashrrev_i32_e32 v67, 31, v66
	v_lshlrev_b64 v[84:85], 11, v[66:67]
	v_lshl_add_u64 v[66:67], v[64:65], 0, v[84:85]
	v_or_b32_e32 v89, 16, v107
	global_load_dwordx4 v[72:75], v[66:67], off
	v_or_b32_e32 v66, s3, v89
	v_ashrrev_i32_e32 v67, 31, v66
	v_lshlrev_b64 v[82:83], 11, v[66:67]
	v_lshl_add_u64 v[66:67], v[64:65], 0, v[82:83]
	v_or_b32_e32 v88, 24, v107
	global_load_dwordx4 v[68:71], v[66:67], off
	v_or_b32_e32 v66, s3, v88
	s_lshl_b32 s3, s2, 16
	v_ashrrev_i32_e32 v67, 31, v66
	s_add_i32 s3, s1, s3
	v_lshlrev_b64 v[80:81], 11, v[66:67]
	s_cmp_lg_u32 s2, 0
	v_lshl_add_u64 v[64:65], v[64:65], 0, v[80:81]
	s_cselect_b64 s[8:9], -1, 0
	global_load_dwordx4 v[64:67], v[64:65], off
	v_lshlrev_b32_e32 v111, 2, v163
	v_add3_u32 v110, s3, v110, v111
	v_cmp_lt_i32_e32 vcc, v222, v219
	s_waitcnt vmcnt(4)
	v_cndmask_b32_e64 v109, 1.0, -v109, s[8:9]
	v_mul_f32_e32 v16, v16, v109
	v_mul_f32_e32 v0, v0, v109
	v_mul_f32_e32 v16, v106, v16
	v_mul_f32_e32 v0, v106, v0
	v_mul_f32_e32 v17, v17, v109
	ds_write2_b32 v110, v16, v0 offset0:64 offset1:96
	v_mul_f32_e32 v0, v1, v109
	v_mul_f32_e32 v48, v48, v109
	v_mul_f32_e32 v32, v32, v109
	v_mul_f32_e32 v17, v105, v17
	v_mul_f32_e32 v0, v105, v0
	v_mul_f32_e32 v48, v106, v48
	v_mul_f32_e32 v32, v106, v32
	v_mul_f32_e32 v18, v18, v109
	ds_write2_b32 v110, v17, v0 offset0:192 offset1:224
	v_mul_f32_e32 v0, v2, v109
	ds_write2_b32 v110, v48, v32 offset1:32
	v_mul_f32_e32 v32, v33, v109
	v_add_u32_e32 v33, 0x400, v110
	v_mul_f32_e32 v18, v104, v18
	v_mul_f32_e32 v0, v104, v0
	v_mul_f32_e32 v49, v49, v109
	v_mul_f32_e32 v19, v19, v109
	ds_write2_b32 v33, v18, v0 offset0:64 offset1:96
	v_mul_f32_e32 v0, v3, v109
	v_mul_f32_e32 v49, v105, v49
	v_mul_f32_e32 v32, v105, v32
	v_mul_f32_e32 v19, v103, v19
	v_mul_f32_e32 v0, v103, v0
	v_mul_f32_e32 v50, v50, v109
	ds_write2_b32 v110, v49, v32 offset0:128 offset1:160
	v_mul_f32_e32 v32, v34, v109
	v_mul_f32_e32 v20, v20, v109
	ds_write2_b32 v33, v19, v0 offset0:192 offset1:224
	v_mul_f32_e32 v0, v4, v109
	v_mul_f32_e32 v50, v104, v50
	v_mul_f32_e32 v32, v104, v32
	v_add_u32_e32 v34, 0x1000, v110
	v_mul_f32_e32 v20, v102, v20
	v_mul_f32_e32 v0, v102, v0
	v_mul_f32_e32 v51, v51, v109
	ds_write2_b32 v33, v50, v32 offset1:32
	v_mul_f32_e32 v32, v35, v109
	v_mul_f32_e32 v21, v21, v109
	ds_write2_b32 v34, v20, v0 offset0:64 offset1:96
	v_mul_f32_e32 v0, v5, v109
	v_mul_f32_e32 v51, v103, v51
	v_mul_f32_e32 v32, v103, v32
	v_mul_f32_e32 v21, v101, v21
	v_mul_f32_e32 v0, v101, v0
	v_mul_f32_e32 v52, v52, v109
	ds_write2_b32 v33, v51, v32 offset0:128 offset1:160
	v_mul_f32_e32 v32, v36, v109
	v_mul_f32_e32 v22, v22, v109
	ds_write2_b32 v34, v21, v0 offset0:192 offset1:224
	v_mul_f32_e32 v0, v6, v109
	v_mul_f32_e32 v52, v102, v52
	v_mul_f32_e32 v32, v102, v32
	v_add_u32_e32 v35, 0x1400, v110
	v_mul_f32_e32 v22, v100, v22
	v_mul_f32_e32 v0, v100, v0
	v_mul_f32_e32 v53, v53, v109
	ds_write2_b32 v34, v52, v32 offset1:32
	v_mul_f32_e32 v32, v37, v109
	v_mul_f32_e32 v23, v23, v109
	ds_write2_b32 v35, v22, v0 offset0:64 offset1:96
	v_mul_f32_e32 v0, v7, v109
	v_mul_f32_e32 v53, v101, v53
	v_mul_f32_e32 v32, v101, v32
	v_mul_f32_e32 v23, v99, v23
	v_mul_f32_e32 v0, v99, v0
	v_mul_f32_e32 v54, v54, v109
	ds_write2_b32 v34, v53, v32 offset0:128 offset1:160
	v_mul_f32_e32 v32, v38, v109
	v_mul_f32_e32 v24, v24, v109
	ds_write2_b32 v35, v23, v0 offset0:192 offset1:224
	v_mul_f32_e32 v0, v8, v109
	v_mul_f32_e32 v54, v100, v54
	v_mul_f32_e32 v32, v100, v32
	v_add_u32_e32 v36, 0x2000, v110
	v_mul_f32_e32 v24, v98, v24
	v_mul_f32_e32 v0, v98, v0
	v_mul_f32_e32 v55, v55, v109
	ds_write2_b32 v35, v54, v32 offset1:32
	v_mul_f32_e32 v32, v39, v109
	v_mul_f32_e32 v25, v25, v109
	ds_write2_b32 v36, v24, v0 offset0:64 offset1:96
	v_mul_f32_e32 v0, v9, v109
	v_mul_f32_e32 v55, v99, v55
	v_mul_f32_e32 v32, v99, v32
	v_mul_f32_e32 v25, v97, v25
	v_mul_f32_e32 v0, v97, v0
	v_mul_f32_e32 v56, v56, v109
	ds_write2_b32 v35, v55, v32 offset0:128 offset1:160
	v_mul_f32_e32 v32, v40, v109
	v_mul_f32_e32 v26, v26, v109
	ds_write2_b32 v36, v25, v0 offset0:192 offset1:224
	v_mul_f32_e32 v0, v10, v109
	v_mul_f32_e32 v56, v98, v56
	v_mul_f32_e32 v32, v98, v32
	v_add_u32_e32 v37, 0x2400, v110
	v_mul_f32_e32 v26, v96, v26
	v_mul_f32_e32 v0, v96, v0
	v_mul_f32_e32 v57, v57, v109
	ds_write2_b32 v36, v56, v32 offset1:32
	v_mul_f32_e32 v32, v41, v109
	v_mul_f32_e32 v27, v27, v109
	ds_write2_b32 v37, v26, v0 offset0:64 offset1:96
	v_mul_f32_e32 v0, v11, v109
	v_mul_f32_e32 v57, v97, v57
	v_mul_f32_e32 v32, v97, v32
	v_mul_f32_e32 v27, v95, v27
	v_mul_f32_e32 v0, v95, v0
	v_mul_f32_e32 v58, v58, v109
	ds_write2_b32 v36, v57, v32 offset0:128 offset1:160
	v_mul_f32_e32 v32, v42, v109
	v_mul_f32_e32 v28, v28, v109
	ds_write2_b32 v37, v27, v0 offset0:192 offset1:224
	v_mul_f32_e32 v0, v12, v109
	v_mul_f32_e32 v58, v96, v58
	v_mul_f32_e32 v32, v96, v32
	v_add_u32_e32 v38, 0x3000, v110
	v_mul_f32_e32 v28, v94, v28
	v_mul_f32_e32 v0, v94, v0
	v_mul_f32_e32 v59, v59, v109
	ds_write2_b32 v37, v58, v32 offset1:32
	v_mul_f32_e32 v32, v43, v109
	v_mul_f32_e32 v29, v29, v109
	ds_write2_b32 v38, v28, v0 offset0:64 offset1:96
	v_mul_f32_e32 v0, v13, v109
	v_mul_f32_e32 v59, v95, v59
	v_mul_f32_e32 v32, v95, v32
	v_mul_f32_e32 v29, v93, v29
	v_mul_f32_e32 v0, v93, v0
	v_mul_f32_e32 v60, v60, v109
	ds_write2_b32 v37, v59, v32 offset0:128 offset1:160
	v_mul_f32_e32 v32, v44, v109
	v_mul_f32_e32 v30, v30, v109
	ds_write2_b32 v38, v29, v0 offset0:192 offset1:224
	v_mul_f32_e32 v0, v14, v109
	v_mul_f32_e32 v60, v94, v60
	v_mul_f32_e32 v32, v94, v32
	v_add_u32_e32 v39, 0x3400, v110
	v_mul_f32_e32 v30, v92, v30
	v_mul_f32_e32 v0, v92, v0
	v_mul_f32_e32 v61, v61, v109
	ds_write2_b32 v38, v60, v32 offset1:32
	v_mul_f32_e32 v32, v45, v109
	v_mul_f32_e32 v31, v31, v109
	ds_write2_b32 v39, v30, v0 offset0:64 offset1:96
	v_mul_f32_e32 v0, v15, v109
	v_mul_f32_e32 v61, v93, v61
	v_mul_f32_e32 v32, v93, v32
	v_mul_f32_e32 v31, v91, v31
	v_mul_f32_e32 v0, v91, v0
	v_mul_f32_e32 v62, v62, v109
	ds_write2_b32 v38, v61, v32 offset0:128 offset1:160
	v_mul_f32_e32 v32, v46, v109
	ds_write2_b32 v39, v31, v0 offset0:192 offset1:224
	v_lshlrev_b32_e32 v18, 2, v108
	v_cndmask_b32_e32 v0, v218, v222, vcc
	v_cmp_lt_i32_e32 vcc, v223, v219
	v_mul_f32_e32 v62, v92, v62
	v_mul_f32_e32 v32, v92, v32
	v_add_u32_e32 v24, s1, v18
	s_add_i32 s1, s1, 0x10000
	v_lshlrev_b32_e32 v19, 2, v0
	v_cndmask_b32_e32 v0, v218, v223, vcc
	v_cmp_lt_i32_e32 vcc, v224, v219
	v_mul_f32_e32 v63, v63, v109
	ds_write2_b32 v39, v62, v32 offset1:32
	v_mul_f32_e32 v32, v47, v109
	v_add_u32_e32 v23, s1, v18
	v_lshlrev_b32_e32 v20, 2, v0
	v_cndmask_b32_e32 v0, v218, v224, vcc
	v_cmp_lt_i32_e32 vcc, v226, v219
	v_lshlrev_b32_e32 v10, 9, v107
	v_mul_f32_e32 v63, v91, v63
	v_mul_f32_e32 v32, v91, v32
	v_lshlrev_b32_e32 v21, 2, v0
	v_cndmask_b32_e32 v0, v218, v226, vcc
	v_add_u32_e32 v4, v24, v10
	v_add_u32_e32 v14, v23, v10
	ds_write2_b32 v39, v63, v32 offset0:128 offset1:160
	s_waitcnt lgkmcnt(0)
	s_barrier
	v_lshlrev_b32_e32 v22, 2, v0
	ds_read_b128 v[0:3], v4
	ds_read_b128 v[4:7], v4 offset:16
	ds_read_b128 v[10:13], v14
	ds_read_b128 v[26:29], v14 offset:16
	s_add_u32 s0, s18, s0
	s_addc_u32 s1, s19, 0
	v_lshl_add_u64 v[8:9], s[0:1], 0, v[194:195]
	s_waitcnt lgkmcnt(1)
	v_pk_add_f32 v[16:17], v[0:1], v[10:11]
	v_pk_add_f32 v[14:15], v[2:3], v[12:13]
	v_mul_f32_e32 v2, v17, v17
	v_fmac_f32_e32 v2, v16, v16
	v_pk_mul_f32 v[0:1], v[14:15], v[14:15]
	s_waitcnt lgkmcnt(0)
	v_pk_add_f32 v[12:13], v[4:5], v[26:27]
	v_add_f32_e32 v0, v0, v2
	v_add_f32_e32 v4, v1, v0
	v_pk_mul_f32 v[2:3], v[12:13], v[12:13]
	v_pk_add_f32 v[10:11], v[6:7], v[28:29]
	v_add_f32_e32 v2, v2, v4
	v_pk_mul_f32 v[0:1], v[10:11], v[10:11]
	v_add_f32_e32 v2, v3, v2
	v_add_f32_e32 v0, v0, v2
	v_add_f32_e32 v0, v1, v0
	ds_bpermute_b32 v1, v19, v0
	s_waitcnt vmcnt(3)
	v_lshlrev_b32_e32 v26, 16, v76
	s_add_i32 s21, s21, s98
	s_add_i32 s20, s20, s67
	s_cmpk_lt_i32 s21, 0x200
	s_waitcnt lgkmcnt(0)
	v_add_f32_e32 v0, v0, v1
	ds_bpermute_b32 v1, v20, v0
	s_waitcnt lgkmcnt(0)
	v_add_f32_e32 v0, v0, v1
	ds_bpermute_b32 v1, v21, v0
	s_waitcnt lgkmcnt(0)
	v_add_f32_e32 v0, v0, v1
	ds_bpermute_b32 v1, v22, v0
	s_waitcnt lgkmcnt(0)
	v_add_f32_e32 v0, v0, v1
	v_fmamk_f32 v0, v0, 0x3c000000, v196
	v_cmp_gt_f32_e32 vcc, s72, v0
	v_mul_f32_e32 v1, 0x4b800000, v0
	s_nop 0
	v_cndmask_b32_e32 v0, v0, v1, vcc
	v_rsq_f32_e32 v0, v0
	s_nop 0
	v_mul_f32_e32 v1, 0x45800000, v0
	v_cndmask_b32_e32 v0, v0, v1, vcc
	v_mul_f32_e32 v25, v162, v0
	global_load_dwordx4 v[0:3], v18, s[6:7] offset:16
	global_load_dwordx4 v[4:7], v18, s[6:7]
	v_mul_f32_e32 v27, v16, v25
	v_mul_f32_e32 v16, 0xbfb8aa3b, v26
	v_exp_f32_e32 v16, v16
	v_mul_f32_e32 v17, v17, v25
	v_mul_f32_e32 v15, v15, v25
	v_add_f32_e32 v16, 1.0, v16
	v_rcp_f32_e32 v28, v16
	v_and_b32_e32 v16, 0xffff0000, v76
	s_waitcnt vmcnt(0)
	v_mov_b32_e32 v29, v4
	v_mul_f32_e32 v4, 0xbfb8aa3b, v16
	v_exp_f32_e32 v4, v4
	v_pk_mul_f32 v[26:27], v[28:29], v[26:27]
	v_add_f32_e32 v4, 1.0, v4
	v_rcp_f32_e32 v4, v4
	v_mul_f32_e32 v26, v26, v27
	v_mov_b32_e32 v27, v6
	v_pk_mul_f32 v[4:5], v[4:5], v[16:17]
	v_mul_f32_e32 v17, v14, v25
	v_lshlrev_b32_e32 v16, 16, v77
	v_and_b32_e32 v14, 0xffff0000, v77
	v_mul_f32_e32 v4, v4, v5
	v_mul_f32_e32 v5, 0xbfb8aa3b, v16
	v_mul_f32_e32 v6, 0xbfb8aa3b, v14
	v_exp_f32_e32 v5, v5
	v_exp_f32_e32 v6, v6
	v_cvt_pk_bf16_f32 v4, v26, v4
	v_add_f32_e32 v5, 1.0, v5
	v_add_f32_e32 v6, 1.0, v6
	v_rcp_f32_e32 v26, v5
	v_rcp_f32_e32 v6, v6
	v_pk_mul_f32 v[16:17], v[26:27], v[16:17]
	v_pk_mul_f32 v[6:7], v[6:7], v[14:15]
	v_mul_f32_e32 v5, v16, v17
	v_mul_f32_e32 v6, v6, v7
	v_cvt_pk_bf16_f32 v5, v5, v6
	v_lshlrev_b32_e32 v6, 16, v78
	v_mul_f32_e32 v7, v12, v25
	v_mul_f32_e32 v12, 0xbfb8aa3b, v6
	v_exp_f32_e32 v12, v12
	v_mov_b32_e32 v15, v0
	v_add_f32_e32 v12, 1.0, v12
	v_rcp_f32_e32 v14, v12
	s_nop 0
	v_pk_mul_f32 v[6:7], v[14:15], v[6:7]
	s_nop 0
	v_mul_f32_e32 v12, v6, v7
	v_and_b32_e32 v6, 0xffff0000, v78
	v_mul_f32_e32 v0, 0xbfb8aa3b, v6
	v_exp_f32_e32 v0, v0
	v_mul_f32_e32 v7, v13, v25
	v_mov_b32_e32 v13, v2
	v_add_f32_e32 v0, 1.0, v0
	v_rcp_f32_e32 v0, v0
	s_nop 0
	v_pk_mul_f32 v[0:1], v[0:1], v[6:7]
	s_nop 0
	v_mul_f32_e32 v0, v0, v1
	v_cvt_pk_bf16_f32 v6, v12, v0
	v_lshlrev_b32_e32 v0, 16, v79
	v_mul_f32_e32 v7, 0xbfb8aa3b, v0
	v_exp_f32_e32 v7, v7
	v_mul_f32_e32 v1, v10, v25
	v_lshlrev_b32_e32 v10, 9, v90
	v_add_u32_e32 v14, v23, v10
	v_add_f32_e32 v7, 1.0, v7
	v_rcp_f32_e32 v12, v7
	s_nop 0
	v_pk_mul_f32 v[0:1], v[12:13], v[0:1]
	s_nop 0
	v_mul_f32_e32 v7, v0, v1
	v_and_b32_e32 v0, 0xffff0000, v79
	v_mul_f32_e32 v2, 0xbfb8aa3b, v0
	v_exp_f32_e32 v2, v2
	v_mul_f32_e32 v1, v11, v25
	v_add_f32_e32 v2, 1.0, v2
	v_rcp_f32_e32 v2, v2
	s_nop 0
	v_pk_mul_f32 v[0:1], v[2:3], v[0:1]
	s_nop 0
	v_mul_f32_e32 v0, v0, v1
	v_cvt_pk_bf16_f32 v7, v7, v0
	v_lshl_add_u64 v[0:1], v[8:9], 0, v[86:87]
	global_store_dwordx4 v[0:1], v[4:7], off
	s_nop 1
	v_add_u32_e32 v4, v24, v10
	ds_read_b128 v[0:3], v4
	ds_read_b128 v[4:7], v4 offset:16
	ds_read_b128 v[10:13], v14
	ds_read_b128 v[26:29], v14 offset:16
	s_waitcnt lgkmcnt(1)
	v_pk_add_f32 v[16:17], v[0:1], v[10:11]
	v_pk_add_f32 v[14:15], v[2:3], v[12:13]
	v_mul_f32_e32 v2, v17, v17
	v_fmac_f32_e32 v2, v16, v16
	v_pk_mul_f32 v[0:1], v[14:15], v[14:15]
	s_waitcnt lgkmcnt(0)
	v_pk_add_f32 v[12:13], v[4:5], v[26:27]
	v_add_f32_e32 v0, v0, v2
	v_add_f32_e32 v4, v1, v0
	v_pk_mul_f32 v[2:3], v[12:13], v[12:13]
	v_pk_add_f32 v[10:11], v[6:7], v[28:29]
	v_add_f32_e32 v2, v2, v4
	v_pk_mul_f32 v[0:1], v[10:11], v[10:11]
	v_add_f32_e32 v2, v3, v2
	v_add_f32_e32 v0, v0, v2
	v_add_f32_e32 v0, v1, v0
	ds_bpermute_b32 v1, v19, v0
	v_lshlrev_b32_e32 v26, 16, v72
	s_waitcnt lgkmcnt(0)
	v_add_f32_e32 v0, v0, v1
	ds_bpermute_b32 v1, v20, v0
	s_waitcnt lgkmcnt(0)
	v_add_f32_e32 v0, v0, v1
	ds_bpermute_b32 v1, v21, v0
	s_waitcnt lgkmcnt(0)
	v_add_f32_e32 v0, v0, v1
	ds_bpermute_b32 v1, v22, v0
	s_waitcnt lgkmcnt(0)
	v_add_f32_e32 v0, v0, v1
	v_fmamk_f32 v0, v0, 0x3c000000, v196
	v_cmp_gt_f32_e32 vcc, s72, v0
	v_mul_f32_e32 v1, 0x4b800000, v0
	s_nop 0
	v_cndmask_b32_e32 v0, v0, v1, vcc
	v_rsq_f32_e32 v0, v0
	s_nop 0
	v_mul_f32_e32 v1, 0x45800000, v0
	v_cndmask_b32_e32 v0, v0, v1, vcc
	v_mul_f32_e32 v25, v162, v0
	global_load_dwordx4 v[0:3], v18, s[6:7] offset:16
	global_load_dwordx4 v[4:7], v18, s[6:7]
	v_mul_f32_e32 v27, v16, v25
	v_mul_f32_e32 v16, 0xbfb8aa3b, v26
	v_exp_f32_e32 v16, v16
	v_mul_f32_e32 v17, v17, v25
	v_mul_f32_e32 v15, v15, v25
	v_add_f32_e32 v16, 1.0, v16
	v_rcp_f32_e32 v28, v16
	v_and_b32_e32 v16, 0xffff0000, v72
	s_waitcnt vmcnt(0)
	v_mov_b32_e32 v29, v4
	v_mul_f32_e32 v4, 0xbfb8aa3b, v16
	v_exp_f32_e32 v4, v4
	v_pk_mul_f32 v[26:27], v[28:29], v[26:27]
	v_add_f32_e32 v4, 1.0, v4
	v_rcp_f32_e32 v4, v4
	v_mul_f32_e32 v26, v26, v27
	v_mov_b32_e32 v27, v6
	v_pk_mul_f32 v[4:5], v[4:5], v[16:17]
	v_mul_f32_e32 v17, v14, v25
	v_lshlrev_b32_e32 v16, 16, v73
	v_and_b32_e32 v14, 0xffff0000, v73
	v_mul_f32_e32 v4, v4, v5
	v_mul_f32_e32 v5, 0xbfb8aa3b, v16
	v_mul_f32_e32 v6, 0xbfb8aa3b, v14
	v_exp_f32_e32 v5, v5
	v_exp_f32_e32 v6, v6
	v_cvt_pk_bf16_f32 v4, v26, v4
	v_add_f32_e32 v5, 1.0, v5
	v_add_f32_e32 v6, 1.0, v6
	v_rcp_f32_e32 v26, v5
	v_rcp_f32_e32 v6, v6
	v_pk_mul_f32 v[16:17], v[26:27], v[16:17]
	v_pk_mul_f32 v[6:7], v[6:7], v[14:15]
	v_mul_f32_e32 v5, v16, v17
	v_mul_f32_e32 v6, v6, v7
	v_cvt_pk_bf16_f32 v5, v5, v6
	v_lshlrev_b32_e32 v6, 16, v74
	v_mul_f32_e32 v7, v12, v25
	v_mul_f32_e32 v12, 0xbfb8aa3b, v6
	v_exp_f32_e32 v12, v12
	v_mov_b32_e32 v15, v0
	v_add_f32_e32 v12, 1.0, v12
	v_rcp_f32_e32 v14, v12
	s_nop 0
	v_pk_mul_f32 v[6:7], v[14:15], v[6:7]
	s_nop 0
	v_mul_f32_e32 v12, v6, v7
	v_and_b32_e32 v6, 0xffff0000, v74
	v_mul_f32_e32 v0, 0xbfb8aa3b, v6
	v_exp_f32_e32 v0, v0
	v_mul_f32_e32 v7, v13, v25
	v_mov_b32_e32 v13, v2
	v_add_f32_e32 v0, 1.0, v0
	v_rcp_f32_e32 v0, v0
	s_nop 0
	v_pk_mul_f32 v[0:1], v[0:1], v[6:7]
	s_nop 0
	v_mul_f32_e32 v0, v0, v1
	v_cvt_pk_bf16_f32 v6, v12, v0
	v_lshlrev_b32_e32 v0, 16, v75
	v_mul_f32_e32 v7, 0xbfb8aa3b, v0
	v_exp_f32_e32 v7, v7
	v_mul_f32_e32 v1, v10, v25
	v_lshlrev_b32_e32 v10, 9, v89
	v_add_u32_e32 v14, v23, v10
	v_add_f32_e32 v7, 1.0, v7
	v_rcp_f32_e32 v12, v7
	s_nop 0
	v_pk_mul_f32 v[0:1], v[12:13], v[0:1]
	s_nop 0
	v_mul_f32_e32 v7, v0, v1
	v_and_b32_e32 v0, 0xffff0000, v75
	v_mul_f32_e32 v2, 0xbfb8aa3b, v0
	v_exp_f32_e32 v2, v2
	v_mul_f32_e32 v1, v11, v25
	v_add_f32_e32 v2, 1.0, v2
	v_rcp_f32_e32 v2, v2
	s_nop 0
	v_pk_mul_f32 v[0:1], v[2:3], v[0:1]
	s_nop 0
	v_mul_f32_e32 v0, v0, v1
	v_cvt_pk_bf16_f32 v7, v7, v0
	v_lshl_add_u64 v[0:1], v[8:9], 0, v[84:85]
	global_store_dwordx4 v[0:1], v[4:7], off
	s_nop 1
	v_add_u32_e32 v4, v24, v10
	ds_read_b128 v[0:3], v4
	ds_read_b128 v[4:7], v4 offset:16
	ds_read_b128 v[10:13], v14
	ds_read_b128 v[26:29], v14 offset:16
	s_waitcnt lgkmcnt(1)
	v_pk_add_f32 v[16:17], v[0:1], v[10:11]
	v_pk_add_f32 v[14:15], v[2:3], v[12:13]
	v_mul_f32_e32 v2, v17, v17
	v_fmac_f32_e32 v2, v16, v16
	v_pk_mul_f32 v[0:1], v[14:15], v[14:15]
	s_waitcnt lgkmcnt(0)
	v_pk_add_f32 v[12:13], v[4:5], v[26:27]
	v_add_f32_e32 v0, v0, v2
	v_add_f32_e32 v4, v1, v0
	v_pk_mul_f32 v[2:3], v[12:13], v[12:13]
	v_pk_add_f32 v[10:11], v[6:7], v[28:29]
	v_add_f32_e32 v2, v2, v4
	v_pk_mul_f32 v[0:1], v[10:11], v[10:11]
	v_add_f32_e32 v2, v3, v2
	v_add_f32_e32 v0, v0, v2
	v_add_f32_e32 v0, v1, v0
	ds_bpermute_b32 v1, v19, v0
	v_lshlrev_b32_e32 v26, 16, v68
	s_waitcnt lgkmcnt(0)
	v_add_f32_e32 v0, v0, v1
	ds_bpermute_b32 v1, v20, v0
	s_waitcnt lgkmcnt(0)
	v_add_f32_e32 v0, v0, v1
	ds_bpermute_b32 v1, v21, v0
	s_waitcnt lgkmcnt(0)
	v_add_f32_e32 v0, v0, v1
	ds_bpermute_b32 v1, v22, v0
	s_waitcnt lgkmcnt(0)
	v_add_f32_e32 v0, v0, v1
	v_fmamk_f32 v0, v0, 0x3c000000, v196
	v_cmp_gt_f32_e32 vcc, s72, v0
	v_mul_f32_e32 v1, 0x4b800000, v0
	s_nop 0
	v_cndmask_b32_e32 v0, v0, v1, vcc
	v_rsq_f32_e32 v0, v0
	s_nop 0
	v_mul_f32_e32 v1, 0x45800000, v0
	v_cndmask_b32_e32 v0, v0, v1, vcc
	v_mul_f32_e32 v25, v162, v0
	global_load_dwordx4 v[0:3], v18, s[6:7] offset:16
	global_load_dwordx4 v[4:7], v18, s[6:7]
	v_mul_f32_e32 v27, v16, v25
	v_mul_f32_e32 v16, 0xbfb8aa3b, v26
	v_exp_f32_e32 v16, v16
	v_mul_f32_e32 v17, v17, v25
	v_mul_f32_e32 v15, v15, v25
	v_add_f32_e32 v16, 1.0, v16
	v_rcp_f32_e32 v28, v16
	v_and_b32_e32 v16, 0xffff0000, v68
	s_waitcnt vmcnt(0)
	v_mov_b32_e32 v29, v4
	v_mul_f32_e32 v4, 0xbfb8aa3b, v16
	v_exp_f32_e32 v4, v4
	v_pk_mul_f32 v[26:27], v[28:29], v[26:27]
	v_add_f32_e32 v4, 1.0, v4
	v_rcp_f32_e32 v4, v4
	v_mul_f32_e32 v26, v26, v27
	v_mov_b32_e32 v27, v6
	v_pk_mul_f32 v[4:5], v[4:5], v[16:17]
	v_mul_f32_e32 v17, v14, v25
	v_lshlrev_b32_e32 v16, 16, v69
	v_and_b32_e32 v14, 0xffff0000, v69
	v_mul_f32_e32 v4, v4, v5
	v_mul_f32_e32 v5, 0xbfb8aa3b, v16
	v_mul_f32_e32 v6, 0xbfb8aa3b, v14
	v_exp_f32_e32 v5, v5
	v_exp_f32_e32 v6, v6
	v_cvt_pk_bf16_f32 v4, v26, v4
	v_add_f32_e32 v5, 1.0, v5
	v_add_f32_e32 v6, 1.0, v6
	v_rcp_f32_e32 v26, v5
	v_rcp_f32_e32 v6, v6
	v_pk_mul_f32 v[16:17], v[26:27], v[16:17]
	v_pk_mul_f32 v[6:7], v[6:7], v[14:15]
	v_mul_f32_e32 v5, v16, v17
	v_mul_f32_e32 v6, v6, v7
	v_cvt_pk_bf16_f32 v5, v5, v6
	v_lshlrev_b32_e32 v6, 16, v70
	v_mul_f32_e32 v7, v12, v25
	v_mul_f32_e32 v12, 0xbfb8aa3b, v6
	v_exp_f32_e32 v12, v12
	v_mov_b32_e32 v15, v0
	v_add_f32_e32 v12, 1.0, v12
	v_rcp_f32_e32 v14, v12
	s_nop 0
	v_pk_mul_f32 v[6:7], v[14:15], v[6:7]
	s_nop 0
	v_mul_f32_e32 v12, v6, v7
	v_and_b32_e32 v6, 0xffff0000, v70
	v_mul_f32_e32 v0, 0xbfb8aa3b, v6
	v_exp_f32_e32 v0, v0
	v_mul_f32_e32 v7, v13, v25
	v_mov_b32_e32 v13, v2
	v_add_f32_e32 v0, 1.0, v0
	v_rcp_f32_e32 v0, v0
	s_nop 0
	v_pk_mul_f32 v[0:1], v[0:1], v[6:7]
	s_nop 0
	v_mul_f32_e32 v0, v0, v1
	v_cvt_pk_bf16_f32 v6, v12, v0
	v_lshlrev_b32_e32 v0, 16, v71
	v_mul_f32_e32 v7, 0xbfb8aa3b, v0
	v_exp_f32_e32 v7, v7
	v_mul_f32_e32 v1, v10, v25
	v_lshlrev_b32_e32 v10, 9, v88
	v_add_u32_e32 v14, v23, v10
	v_add_f32_e32 v7, 1.0, v7
	v_rcp_f32_e32 v12, v7
	s_nop 0
	v_pk_mul_f32 v[0:1], v[12:13], v[0:1]
	s_nop 0
	v_mul_f32_e32 v7, v0, v1
	v_and_b32_e32 v0, 0xffff0000, v71
	v_mul_f32_e32 v2, 0xbfb8aa3b, v0
	v_exp_f32_e32 v2, v2
	v_mul_f32_e32 v1, v11, v25
	v_add_f32_e32 v2, 1.0, v2
	v_rcp_f32_e32 v2, v2
	s_nop 0
	v_pk_mul_f32 v[0:1], v[2:3], v[0:1]
	s_nop 0
	v_mul_f32_e32 v0, v0, v1
	v_cvt_pk_bf16_f32 v7, v7, v0
	v_lshl_add_u64 v[0:1], v[8:9], 0, v[82:83]
	global_store_dwordx4 v[0:1], v[4:7], off
	s_nop 1
	v_add_u32_e32 v4, v24, v10
	ds_read_b128 v[0:3], v4
	ds_read_b128 v[4:7], v4 offset:16
	ds_read_b128 v[10:13], v14
	ds_read_b128 v[24:27], v14 offset:16
	s_waitcnt lgkmcnt(1)
	v_pk_add_f32 v[16:17], v[0:1], v[10:11]
	v_pk_add_f32 v[14:15], v[2:3], v[12:13]
	v_mul_f32_e32 v2, v17, v17
	v_fmac_f32_e32 v2, v16, v16
	v_pk_mul_f32 v[0:1], v[14:15], v[14:15]
	s_waitcnt lgkmcnt(0)
	v_pk_add_f32 v[12:13], v[4:5], v[24:25]
	v_add_f32_e32 v0, v0, v2
	v_add_f32_e32 v4, v1, v0
	v_pk_mul_f32 v[2:3], v[12:13], v[12:13]
	v_pk_add_f32 v[10:11], v[6:7], v[26:27]
	v_add_f32_e32 v2, v2, v4
	v_pk_mul_f32 v[0:1], v[10:11], v[10:11]
	v_add_f32_e32 v2, v3, v2
	v_add_f32_e32 v0, v0, v2
	v_add_f32_e32 v0, v1, v0
	ds_bpermute_b32 v1, v19, v0
	s_waitcnt lgkmcnt(0)
	v_add_f32_e32 v0, v0, v1
	ds_bpermute_b32 v1, v20, v0
	v_lshlrev_b32_e32 v20, 16, v64
	s_waitcnt lgkmcnt(0)
	v_add_f32_e32 v0, v0, v1
	ds_bpermute_b32 v1, v21, v0
	s_waitcnt lgkmcnt(0)
	v_add_f32_e32 v0, v0, v1
	ds_bpermute_b32 v1, v22, v0
	s_waitcnt lgkmcnt(0)
	v_add_f32_e32 v0, v0, v1
	v_fmamk_f32 v0, v0, 0x3c000000, v196
	v_cmp_gt_f32_e32 vcc, s72, v0
	v_mul_f32_e32 v1, 0x4b800000, v0
	s_nop 0
	v_cndmask_b32_e32 v0, v0, v1, vcc
	v_rsq_f32_e32 v0, v0
	s_nop 0
	v_mul_f32_e32 v1, 0x45800000, v0
	v_cndmask_b32_e32 v0, v0, v1, vcc
	v_mul_f32_e32 v19, v162, v0
	global_load_dwordx4 v[0:3], v18, s[6:7] offset:16
	global_load_dwordx4 v[4:7], v18, s[6:7]
	v_mul_f32_e32 v21, v16, v19
	v_mul_f32_e32 v16, 0xbfb8aa3b, v20
	v_exp_f32_e32 v16, v16
	v_mul_f32_e32 v17, v17, v19
	v_mul_f32_e32 v15, v15, v19
	v_add_f32_e32 v16, 1.0, v16
	v_rcp_f32_e32 v22, v16
	v_and_b32_e32 v16, 0xffff0000, v64
	s_waitcnt vmcnt(0)
	v_mov_b32_e32 v23, v4
	v_mul_f32_e32 v4, 0xbfb8aa3b, v16
	v_exp_f32_e32 v4, v4
	v_pk_mul_f32 v[20:21], v[22:23], v[20:21]
	v_add_f32_e32 v4, 1.0, v4
	v_rcp_f32_e32 v4, v4
	v_mul_f32_e32 v18, v20, v21
	v_mov_b32_e32 v21, v6
	v_pk_mul_f32 v[4:5], v[4:5], v[16:17]
	v_mul_f32_e32 v17, v14, v19
	v_lshlrev_b32_e32 v16, 16, v65
	v_and_b32_e32 v14, 0xffff0000, v65
	v_mul_f32_e32 v4, v4, v5
	v_mul_f32_e32 v5, 0xbfb8aa3b, v16
	v_mul_f32_e32 v6, 0xbfb8aa3b, v14
	v_exp_f32_e32 v5, v5
	v_exp_f32_e32 v6, v6
	v_cvt_pk_bf16_f32 v4, v18, v4
	v_add_f32_e32 v5, 1.0, v5
	v_add_f32_e32 v6, 1.0, v6
	v_rcp_f32_e32 v20, v5
	v_rcp_f32_e32 v6, v6
	v_pk_mul_f32 v[16:17], v[20:21], v[16:17]
	v_pk_mul_f32 v[6:7], v[6:7], v[14:15]
	v_mul_f32_e32 v5, v16, v17
	v_mul_f32_e32 v6, v6, v7
	v_cvt_pk_bf16_f32 v5, v5, v6
	v_lshlrev_b32_e32 v6, 16, v66
	v_mul_f32_e32 v7, v12, v19
	v_mul_f32_e32 v12, 0xbfb8aa3b, v6
	v_exp_f32_e32 v12, v12
	v_mov_b32_e32 v15, v0
	v_add_f32_e32 v12, 1.0, v12
	v_rcp_f32_e32 v14, v12
	s_nop 0
	v_pk_mul_f32 v[6:7], v[14:15], v[6:7]
	s_nop 0
	v_mul_f32_e32 v12, v6, v7
	v_and_b32_e32 v6, 0xffff0000, v66
	v_mul_f32_e32 v0, 0xbfb8aa3b, v6
	v_exp_f32_e32 v0, v0
	v_mul_f32_e32 v7, v13, v19
	v_mov_b32_e32 v13, v2
	v_add_f32_e32 v0, 1.0, v0
	v_rcp_f32_e32 v0, v0
	s_nop 0
	v_pk_mul_f32 v[0:1], v[0:1], v[6:7]
	s_nop 0
	v_mul_f32_e32 v0, v0, v1
	v_cvt_pk_bf16_f32 v6, v12, v0
	v_lshlrev_b32_e32 v0, 16, v67
	v_mul_f32_e32 v7, 0xbfb8aa3b, v0
	v_exp_f32_e32 v7, v7
	v_mul_f32_e32 v1, v10, v19
	v_add_f32_e32 v7, 1.0, v7
	v_rcp_f32_e32 v12, v7
	s_nop 0
	v_pk_mul_f32 v[0:1], v[12:13], v[0:1]
	s_nop 0
	v_mul_f32_e32 v7, v0, v1
	v_and_b32_e32 v0, 0xffff0000, v67
	v_mul_f32_e32 v2, 0xbfb8aa3b, v0
	v_exp_f32_e32 v2, v2
	v_mul_f32_e32 v1, v11, v19
	v_add_f32_e32 v2, 1.0, v2
	v_rcp_f32_e32 v2, v2
	s_nop 0
	v_pk_mul_f32 v[0:1], v[2:3], v[0:1]
	s_nop 0
	v_mul_f32_e32 v0, v0, v1
	v_cvt_pk_bf16_f32 v7, v7, v0
	v_lshl_add_u64 v[0:1], v[8:9], 0, v[80:81]
	global_store_dwordx4 v[0:1], v[4:7], off
	s_barrier
	s_cbranch_scc0 .LBB0_484
	s_cmp_eq_u32 s32, 4
	s_cbranch_scc1 .LBB0_484

.LBB0_484:
	s_cmp_ge_u32 s32, 16
	s_cbranch_scc1 .Lat_end
	v_readlane_b32 s0, v253, 36
	v_readlane_b32 s1, v253, 37
	s_andn2_b64 vcc, exec, s[0:1]
	s_cbranch_vccnz .LBB0_506
	s_add_u32 s0, s76, 0x7800000
	s_addc_u32 s1, s77, 0
	s_add_u32 s2, s76, 0x4800000
	s_addc_u32 s3, s77, 0
	s_add_u32 s16, s76, 0x3000000
	s_addc_u32 s17, s77, 0
	s_add_u32 s6, s76, 0x10900000
	s_addc_u32 s7, s77, 0
	s_mov_b32 s18, s52
	s_branch .LBB0_487

.LBB0_530:
	s_cmp_eq_u32 s32, 1
	s_cbranch_scc0 .Lat_h3b
	s_mov_b32 s32, 16
	s_branch .Lat_A
.Lat_h3b:
	s_cmp_eq_u32 s32, 4
	s_cbranch_scc0 .Lat_end
	s_mov_b32 s32, 17
	s_branch .Lat_A
